# grid barrier: follower workgroups poll the top-level generation word directly, per-XCD generation bump dropped
# speedup vs baseline: 1.0122x; 1.0029x over previous
; DI unsigned xb_ld(unsigned* p)              { return __hip_atomic_load(p, __ATOMIC_RELAXED, __HIP_MEMORY_SCOPE_AGENT); }
; DI unsigned xb_add(unsigned* p, unsigned v) { return __hip_atomic_fetch_add(p, v, __ATOMIC_RELAXED, __HIP_MEMORY_SCOPE_AGENT); }
; #define XB_SPIN(cond, bar) do { unsigned _sp = 0; while (cond) { __builtin_amdgcn_s_sleep(1); \
;     if ((++_sp & 255u) == 0u) { if (xb_ld(&(bar)[XB_TMO])) break; if (_sp > XB_SPIN_CAP) { atomicAdd(&(bar)[XB_TMO], 1u); break; } } } } while (0)
; DI void xcd_barrier(const XcdBarrier& b) {
;     ...
;         const unsigned old = xb_add(&bar[XB_XSUB(b.x)], 1u);
;         const unsigned gen = old / nloc;
;         if (old + 1u == (gen + 1u) * nloc) {
;             __builtin_amdgcn_fence(__ATOMIC_RELEASE, "agent");
;             asm volatile("s_waitcnt vmcnt(0)" ::: "memory");
;             const unsigned og = xb_add(&bar[XB_TOP], 1u);
;             const unsigned tg = og / nx;
;             if (og + 1u == (tg + 1u) * nx) xb_add(&bar[XB_TOPGEN], 1u);
;             else XB_SPIN(xb_ld(&bar[XB_TOPGEN]) == tg, bar);
;             __builtin_amdgcn_fence(__ATOMIC_ACQUIRE, "agent");
;             xb_add(&bar[XB_XGEN(b.x)], 1u);
;             asm volatile("s_waitcnt vmcnt(0)" ::: "memory");
;         } else {
;             XB_SPIN(xb_ld(&bar[XB_XGEN(b.x)]) == gen, bar);
.LBB0_1678:
	s_or_b64 exec, exec, s[4:5]
	v_cvt_f32_u32_e32 v4, v2
	s_waitcnt vmcnt(0)
	v_readfirstlane_b32 s4, v3
	v_sub_u32_e32 v3, 0, v2
	v_rcp_iflag_f32_e32 v4, v4
	v_add_u32_e32 v5, s4, v1
	v_mul_f32_e32 v4, 0x4f7ffffe, v4
	v_cvt_u32_f32_e32 v4, v4
	v_mul_lo_u32 v1, v3, v4
	v_mul_hi_u32 v1, v4, v1
	v_add_u32_e32 v1, v4, v1
	v_mul_hi_u32 v1, v5, v1
	v_mul_lo_u32 v3, v1, v2
	v_sub_u32_e32 v3, v5, v3
	v_add_u32_e32 v4, 1, v1
	v_cmp_ge_u32_e32 vcc, v3, v2
	s_nop 1
	v_cndmask_b32_e32 v1, v1, v4, vcc
	v_sub_u32_e32 v4, v3, v2
	v_cndmask_b32_e32 v3, v3, v4, vcc
	v_add_u32_e32 v4, 1, v1
	v_cmp_ge_u32_e32 vcc, v3, v2
	v_add_u32_e32 v3, 1, v5
	s_nop 0
	v_cndmask_b32_e32 v1, v1, v4, vcc
	v_mul_lo_u32 v4, v2, v1
	v_add_u32_e32 v2, v4, v2
	v_cmp_ne_u32_e32 vcc, v3, v2
	s_and_saveexec_b64 s[4:5], vcc
	s_xor_b64 s[4:5], exec, s[4:5]
	s_cbranch_execz .LBB0_1692
	v_readlane_b32 s6, v252, 61
	v_readlane_b32 s7, v252, 62
	s_waitcnt lgkmcnt(0)
	s_nop 3
	global_load_dword v0, v181, s[6:7] sc1
	s_waitcnt vmcnt(0)
	v_cmp_eq_u32_e32 vcc, v0, v1
	s_and_saveexec_b64 s[6:7], vcc
	s_cbranch_execz .LBB0_1691
	s_mov_b32 s18, 1
	s_mov_b64 s[8:9], 0
	s_branch .LBB0_1682

; DI unsigned xb_ld(unsigned* p)              { return __hip_atomic_load(p, __ATOMIC_RELAXED, __HIP_MEMORY_SCOPE_AGENT); }
; #define XB_SPIN(cond, bar) do { unsigned _sp = 0; while (cond) { __builtin_amdgcn_s_sleep(1); \
;     if ((++_sp & 255u) == 0u) { if (xb_ld(&(bar)[XB_TMO])) break; if (_sp > XB_SPIN_CAP) { atomicAdd(&(bar)[XB_TMO], 1u); break; } } } } while (0)
; DI void xcd_barrier(const XcdBarrier& b) {
;     ...
;             XB_SPIN(xb_ld(&bar[XB_XGEN(b.x)]) == gen, bar);
.LBB0_1684:
	v_readlane_b32 s12, v252, 61
	v_readlane_b32 s13, v252, 62
	s_add_i32 s18, s18, 1
	s_mov_b64 s[14:15], -1
	s_nop 2
	global_load_dword v0, v181, s[12:13] sc1
	s_waitcnt vmcnt(0)
	v_cmp_ne_u32_e32 vcc, v0, v1
	s_orn2_b64 s[12:13], vcc, exec
	s_branch .LBB0_1681

; DI unsigned xb_add(unsigned* p, unsigned v) { return __hip_atomic_fetch_add(p, v, __ATOMIC_RELAXED, __HIP_MEMORY_SCOPE_AGENT); }
; DI void xcd_barrier(const XcdBarrier& b) {
;     ...
;             __builtin_amdgcn_fence(__ATOMIC_ACQUIRE, "agent");
;             xb_add(&bar[XB_XGEN(b.x)], 1u);
;             asm volatile("s_waitcnt vmcnt(0)" ::: "memory");
.LBB0_1710:
	s_getpc_b64 s[98:99]
